# G1+A1+nt13+V2 + small stagger: waves 4-7 s_sleep 2 after each attention tile barrier
# speedup vs baseline: 1.0108x; 1.0023x over previous
; __device__ __forceinline__ void attn_unit256q(const bf16* __restrict__ Qb, const unsigned char* __restrict__ Kc, const unsigned char* __restrict__ Kl, const float* __restrict__ Sc, const float* __restrict__ Sl, ...
;     ...
;   float ksn0 = Sc[0], ksn1 = Sc[1];
;   constexpr float BIAS = 12582912.f;
;   i32x16 bini;
; #pragma unroll
;   for (int r = 0; r < 16; ++r) bini[r] = 0x4B400000;
;   asm volatile("" : "+v"(bini));
;   float m_reg = -1e30f, l_reg = 0.f, alpha = 1.f; f32x16 o[8];
; #pragma unroll
;   for (int d = 0; d < 8; ++d) o[d] = f32x16{};
;   f32x16 p; i32x16 p8; bf16x8 pa0, pa1; float ks0, ks1;
.LBB0_527:
	s_or_b64 exec, exec, s[0:1]
	s_add_u32 s22, s30, 0x1ca00000
	v_readlane_b32 s0, v243, 50
	s_addc_u32 s23, s31, 0
	s_ashr_i32 s24, s33, 31
	s_ashr_i32 s25, s0, 31
	s_mov_b32 s5, 0
	v_mov_b64_e32 v[198:199], 0x87f
	v_mov_b32_e32 v201, 0
	s_mov_b32 s26, 0x41000000
	s_mov_b32 s27, 0x42fe0000
	s_mov_b32 s34, 0x40c0c00
	s_mov_b64 s[6:7], 0x80
	s_mov_b64 s[8:9], 0x100
	s_mov_b64 s[10:11], 0x180
	v_mov_b64_e32 v[202:203], 0x7ff
	v_mov_b32_e32 v217, 0x7ffff3
	s_waitcnt lgkmcnt(0)
	v_mov_b32_e32 v2, 0x4b400000
	v_readlane_b32 s98, v243, 0
	s_nop 3
	s_cmp_ge_u32 s98, 4
	s_cselect_b64 s[98:99], -1, 0
	s_mov_b32 s100, 0x4b400000
	s_mov_b32 s35, 0
	s_barrier
	s_branch .LBB0_530

.LBB0_538:
	s_add_i32 s2, s79, -1
	s_min_u32 s85, s2, s84
	s_lshl_b32 s4, s85, 6
	s_cmp_lt_u32 s85, 4
	s_cselect_b64 s[2:3], -1, 0
	s_add_i32 s88, s4, 0xffffff00
	s_and_b64 s[86:87], s[2:3], exec
	s_cselect_b32 s4, s4, s88
	s_cselect_b32 s88, s17, s73
	s_cselect_b32 s89, s16, s72
	s_lshl_b64 s[86:87], s[4:5], 7
	s_add_u32 s86, s89, s86
	s_addc_u32 s87, s88, s87
	s_lshl_b32 s88, s85, 1
	s_mov_b32 s89, s5
	s_lshl_b64 s[88:89], s[88:89], 2
	s_add_u32 s85, s18, s88
	s_addc_u32 s90, s19, s89
	s_add_u32 s88, s74, s88
	s_addc_u32 s89, s75, s89
	s_add_u32 s88, s88, 0xffffffe0
	s_addc_u32 s89, s89, -1
	s_and_b64 s[2:3], s[2:3], exec
	s_cselect_b32 s3, s90, s89
	s_cselect_b32 s2, s85, s88
	s_waitcnt vmcnt(0) lgkmcnt(0)
	s_barrier
	s_mov_b64 vcc, s[98:99]
	s_cbranch_vccz .Lstg_a
	s_sleep 2
.Lstg_a:
	s_waitcnt vmcnt(0)
	global_load_dwordx2 v[208:209], v201, s[2:3]
	s_cselect_b32 s85, s21, s77
	s_cselect_b32 s88, s20, s76
	s_lshl_b64 s[2:3], s[4:5], 9
	s_add_u32 s2, s88, s2
	ds_read_b128 v[180:183], v225
	ds_read_b128 v[184:187], v226
	s_addc_u32 s3, s85, s3
	s_cmp_lg_u32 0, -1
	s_cselect_b32 s4, 0, 0
	s_add_i32 s85, s4, s80
	s_add_i32 s4, s4, s81
	s_addk_i32 s85, 0x4000
	s_add_i32 s88, s4, 0x10000
	s_waitcnt lgkmcnt(1)
	v_mfma_i32_32x32x32_i8 v[148:163], v[180:183], v[164:167], v[132:147]
	ds_read_b128 v[180:183], v227
	v_lshl_add_u64 v[188:189], s[86:87], 0, v[200:201]
	s_mov_b32 s86, m0
	s_mov_b32 m0, s85
	s_nop 0
	global_load_lds_dwordx4 v[188:189], off
	s_mov_b32 m0, s86
	v_lshl_add_u64 v[192:193], s[2:3], 0, v[204:205]
	s_mov_b32 s2, m0
	s_mov_b32 m0, s88
	s_nop 0
	global_load_lds_dwordx4 v[192:193], off
	s_mov_b32 m0, s2
	s_waitcnt lgkmcnt(1)
	v_mfma_i32_32x32x32_i8 v[148:163], v[184:187], v[168:171], v[148:163]
	ds_read_b128 v[188:191], v228
	v_lshl_add_u64 v[184:185], v[192:193], 0, s[6:7]
	s_add_i32 s2, s4, 0x10400
	s_mov_b32 s3, m0
	s_mov_b32 m0, s2
	s_nop 0
	global_load_lds_dwordx4 v[184:185], off
	s_mov_b32 m0, s3
	v_lshl_add_u64 v[184:185], v[192:193], 0, s[8:9]
	s_add_i32 s2, s4, 0x10800
	s_mov_b32 s3, m0
	s_mov_b32 m0, s2
	s_nop 0
	global_load_lds_dwordx4 v[184:185], off
	s_mov_b32 m0, s3
	s_waitcnt lgkmcnt(1)
	v_mfma_i32_32x32x32_i8 v[148:163], v[180:183], v[172:175], v[148:163]
	v_lshl_add_u64 v[180:181], v[192:193], 0, s[10:11]
	s_add_i32 s4, s4, 0x10c00
	s_mov_b32 s2, m0
	s_mov_b32 m0, s4
	s_nop 0
	global_load_lds_dwordx4 v[180:181], off
	s_mov_b32 m0, s2
	ds_read_b64_tr_b16 v[184:185], v3 offset:32768
	ds_read_b64_tr_b16 v[186:187], v3 offset:36864
	s_waitcnt lgkmcnt(2)
	v_mfma_i32_32x32x32_i8 v[148:163], v[188:191], v[176:179], v[148:163]
	ds_read_b64_tr_b16 v[180:181], v3 offset:33280
	ds_read_b64_tr_b16 v[182:183], v3 offset:37376
	s_nop 9
	v_max3_f32 v188, v148, v149, v150
	v_max3_f32 v189, v151, v152, v153
	v_max3_f32 v190, v154, v155, v156
	v_max3_f32 v191, v157, v158, v159
	v_max3_f32 v192, v160, v161, v162
	v_max3_f32 v188, v188, v189, v190
	v_max3_f32 v191, v191, v192, v163
	v_max_f32_e32 v188, v188, v191
	v_add_f32_e32 v188, 0xcb400000, v188
	v_fma_f32 v189, v206, v188, -v237
	v_cmp_gt_f32_e32 vcc, v189, v220
	s_cbranch_vccnz .Lv2_rare_h1

.Lv2_back_h2:
	v_mul_f32_e32 v189, v221, v207
	v_fma_f32 v190, s100, v189, v255
	v_fma_f32 v148, v148, v189, -v190
	v_fma_f32 v149, v149, v189, -v190
	v_exp_f32_e32 v148, v148
	v_fma_f32 v150, v150, v189, -v190
	v_exp_f32_e32 v149, v149
	v_fma_f32 v151, v151, v189, -v190
	v_exp_f32_e32 v150, v150
	v_fma_f32 v152, v152, v189, -v190
	v_exp_f32_e32 v151, v151
	v_fma_f32 v153, v153, v189, -v190
	v_exp_f32_e32 v152, v152
	v_fma_f32 v154, v154, v189, -v190
	v_exp_f32_e32 v153, v153
	v_fma_f32 v155, v155, v189, -v190
	v_exp_f32_e32 v154, v154
	v_fma_f32 v156, v156, v189, -v190
	v_exp_f32_e32 v155, v155
	v_fma_f32 v157, v157, v189, -v190
	v_exp_f32_e32 v156, v156
	v_fma_f32 v158, v158, v189, -v190
	v_exp_f32_e32 v157, v157
	v_fma_f32 v159, v159, v189, -v190
	v_exp_f32_e32 v158, v158
	v_fma_f32 v160, v160, v189, -v190
	v_exp_f32_e32 v159, v159
	v_fma_f32 v161, v161, v189, -v190
	v_exp_f32_e32 v160, v160
	v_fma_f32 v162, v162, v189, -v190
	v_exp_f32_e32 v161, v161
	v_fma_f32 v163, v163, v189, -v190
	v_exp_f32_e32 v162, v162
	v_exp_f32_e32 v163, v163
	v_add_f32_e32 v188, v148, v149
	v_add_f32_e32 v189, v150, v151
	v_add_f32_e32 v190, v152, v153
	v_add_f32_e32 v191, v154, v155
	v_add_f32_e32 v192, v156, v157
	v_add_f32_e32 v193, v158, v159
	v_add_f32_e32 v194, v160, v161
	v_add_f32_e32 v195, v162, v163
	v_add_f32_e32 v188, v188, v189
	v_add_f32_e32 v190, v190, v191
	v_add_f32_e32 v192, v192, v193
	v_add_f32_e32 v194, v194, v195
	v_add_f32_e32 v188, v188, v190
	v_add_f32_e32 v192, v192, v194
	v_add_f32_e32 v188, v188, v192
	v_add_f32_e32 v224, v224, v188
	v_cvt_pk_bf16_f32 v155, v154, v155
	v_cvt_pk_bf16_f32 v154, v152, v153
	v_cvt_pk_bf16_f32 v152, v148, v149
	v_cvt_pk_bf16_f32 v153, v150, v151
	v_cvt_pk_bf16_f32 v148, v156, v157
	v_cvt_pk_bf16_f32 v149, v158, v159
	v_cvt_pk_bf16_f32 v150, v160, v161
	v_cvt_pk_bf16_f32 v151, v162, v163
	s_waitcnt lgkmcnt(2)
	v_mfma_f32_32x32x16_bf16 v[4:19], v[152:155], v[184:187], v[4:19]
	ds_read_b64_tr_b16 v[156:157], v3 offset:50176
	ds_read_b64_tr_b16 v[158:159], v3 offset:54272
	s_waitcnt lgkmcnt(2)
	v_mfma_f32_32x32x16_bf16 v[116:131], v[152:155], v[180:183], v[116:131]
	ds_read_b64_tr_b16 v[160:161], v3 offset:50688
	ds_read_b64_tr_b16 v[162:163], v3 offset:54784
	s_waitcnt lgkmcnt(2)
	v_mfma_f32_32x32x16_bf16 v[100:115], v[152:155], v[156:159], v[100:115]
	ds_read_b64_tr_b16 v[156:157], v3 offset:51200
	ds_read_b64_tr_b16 v[158:159], v3 offset:55296
	s_waitcnt lgkmcnt(2)
	v_mfma_f32_32x32x16_bf16 v[84:99], v[152:155], v[160:163], v[84:99]
	ds_read_b64_tr_b16 v[160:161], v3 offset:51712
	ds_read_b64_tr_b16 v[162:163], v3 offset:55808
	s_waitcnt lgkmcnt(2)
	v_mfma_f32_32x32x16_bf16 v[68:83], v[152:155], v[156:159], v[68:83]
	ds_read_b64_tr_b16 v[156:157], v3 offset:52224
	ds_read_b64_tr_b16 v[158:159], v3 offset:56320
	s_waitcnt lgkmcnt(2)
	v_mfma_f32_32x32x16_bf16 v[52:67], v[152:155], v[160:163], v[52:67]
	ds_read_b64_tr_b16 v[160:161], v3 offset:52736
	ds_read_b64_tr_b16 v[162:163], v3 offset:56832
	s_waitcnt lgkmcnt(2)
	v_mfma_f32_32x32x16_bf16 v[36:51], v[152:155], v[156:159], v[36:51]
	ds_read_b64_tr_b16 v[156:157], v3 offset:57344
	ds_read_b64_tr_b16 v[158:159], v3 offset:61440
	s_waitcnt lgkmcnt(2)
	v_mfma_f32_32x32x16_bf16 v[20:35], v[152:155], v[160:163], v[20:35]
	ds_read_b64_tr_b16 v[152:153], v3 offset:57856
	ds_read_b64_tr_b16 v[154:155], v3 offset:61952
	s_waitcnt lgkmcnt(2)
	v_mfma_f32_32x32x16_bf16 v[4:19], v[148:151], v[156:159], v[4:19]
	ds_read_b64_tr_b16 v[156:157], v3 offset:58368
	ds_read_b64_tr_b16 v[158:159], v3 offset:62464
	s_waitcnt lgkmcnt(2)
	v_mfma_f32_32x32x16_bf16 v[116:131], v[148:151], v[152:155], v[116:131]
	ds_read_b64_tr_b16 v[152:153], v3 offset:58880
	ds_read_b64_tr_b16 v[154:155], v3 offset:62976
	s_waitcnt lgkmcnt(2)
	v_mfma_f32_32x32x16_bf16 v[100:115], v[148:151], v[156:159], v[100:115]
	ds_read_b64_tr_b16 v[156:157], v3 offset:59392
	ds_read_b64_tr_b16 v[158:159], v3 offset:63488
	s_waitcnt lgkmcnt(2)
	v_mfma_f32_32x32x16_bf16 v[84:99], v[148:151], v[152:155], v[84:99]
	ds_read_b64_tr_b16 v[152:153], v3 offset:59904
	ds_read_b64_tr_b16 v[154:155], v3 offset:64000
	s_waitcnt lgkmcnt(2)
	v_mfma_f32_32x32x16_bf16 v[68:83], v[148:151], v[156:159], v[68:83]
	ds_read_b64_tr_b16 v[156:157], v3 offset:60416
	ds_read_b64_tr_b16 v[158:159], v3 offset:64512
	s_waitcnt lgkmcnt(2)
	v_mfma_f32_32x32x16_bf16 v[52:67], v[148:151], v[152:155], v[52:67]
	ds_read_b64_tr_b16 v[152:153], v3 offset:60928
	ds_read_b64_tr_b16 v[154:155], v3 offset:65024
	s_waitcnt lgkmcnt(2)
	v_mfma_f32_32x32x16_bf16 v[36:51], v[148:151], v[156:159], v[36:51]
	s_waitcnt lgkmcnt(0)
	v_mfma_f32_32x32x16_bf16 v[20:35], v[148:151], v[152:155], v[20:35]
	s_min_u32 s85, s79, s84
	s_lshl_b32 s4, s85, 6
	s_cmp_lt_u32 s85, 4
	s_cselect_b64 s[2:3], -1, 0
	s_add_i32 s88, s4, 0xffffff00
	s_and_b64 s[86:87], s[2:3], exec
	s_cselect_b32 s4, s4, s88
	s_cselect_b32 s88, s17, s73
	s_cselect_b32 s89, s16, s72
	s_lshl_b64 s[86:87], s[4:5], 7
	s_add_u32 s86, s89, s86
	s_addc_u32 s87, s88, s87
	s_lshl_b32 s88, s85, 1
	s_mov_b32 s89, s5
	s_lshl_b64 s[88:89], s[88:89], 2
	s_add_u32 s85, s18, s88
	s_addc_u32 s90, s19, s89
	s_add_u32 s88, s74, s88
	s_addc_u32 s89, s75, s89
	s_add_u32 s88, s88, 0xffffffe0
	s_addc_u32 s89, s89, -1
	s_and_b64 s[2:3], s[2:3], exec
	s_waitcnt vmcnt(0)
	v_mov_b32_e32 v236, v209
	s_cselect_b32 s3, s90, s89
	s_cselect_b32 s2, s85, s88
	s_waitcnt vmcnt(0) lgkmcnt(0)
	s_barrier
	s_mov_b64 vcc, s[98:99]
	s_cbranch_vccz .Lstg_b
	s_sleep 2
.Lstg_b:
	global_load_dwordx2 v[206:207], v201, s[2:3]
	ds_read_b128 v[180:183], v225 offset:16384
	ds_read_b128 v[184:187], v226 offset:16384
	s_cselect_b32 s85, s21, s77
	s_cselect_b32 s88, s20, s76
	s_lshl_b64 s[2:3], s[4:5], 9
	s_add_u32 s2, s88, s2
	s_addc_u32 s3, s85, s3
	s_waitcnt lgkmcnt(1)
	v_mfma_i32_32x32x32_i8 v[148:163], v[180:183], v[164:167], v[132:147]
	ds_read_b128 v[180:183], v227 offset:16384
	v_lshl_add_u64 v[188:189], s[86:87], 0, v[200:201]
	s_mov_b32 s4, m0
	s_mov_b32 m0, s83
	s_nop 0
	global_load_lds_dwordx4 v[188:189], off
	s_mov_b32 m0, s4
	v_lshl_add_u64 v[192:193], s[2:3], 0, v[204:205]
	s_mov_b32 s2, m0
	s_mov_b32 m0, s82
	s_nop 0
	global_load_lds_dwordx4 v[192:193], off
	s_mov_b32 m0, s2
	s_waitcnt lgkmcnt(1)
	v_mfma_i32_32x32x32_i8 v[148:163], v[184:187], v[168:171], v[148:163]
	ds_read_b128 v[188:191], v228 offset:16384
	v_lshl_add_u64 v[184:185], v[192:193], 0, s[6:7]
	s_add_i32 s2, s82, 0x400
	s_mov_b32 s3, m0
	s_mov_b32 m0, s2
	s_nop 0
	global_load_lds_dwordx4 v[184:185], off
	s_mov_b32 m0, s3
	v_lshl_add_u64 v[184:185], v[192:193], 0, s[8:9]
	s_add_i32 s2, s82, 0x800
	s_mov_b32 s3, m0
	s_mov_b32 m0, s2
	s_nop 0
	global_load_lds_dwordx4 v[184:185], off
	s_mov_b32 m0, s3
	s_waitcnt lgkmcnt(1)
	v_mfma_i32_32x32x32_i8 v[148:163], v[180:183], v[172:175], v[148:163]
	v_lshl_add_u64 v[180:181], v[192:193], 0, s[10:11]
	s_add_i32 s2, s82, 0xc00
	s_mov_b32 s3, m0
	s_mov_b32 m0, s2
	s_nop 0
	global_load_lds_dwordx4 v[180:181], off
	s_mov_b32 m0, s3
	ds_read_b64_tr_b16 v[184:185], v222 offset:32768
	ds_read_b64_tr_b16 v[186:187], v222 offset:36864
	s_waitcnt lgkmcnt(2)
	v_mfma_i32_32x32x32_i8 v[148:163], v[188:191], v[176:179], v[148:163]
	ds_read_b64_tr_b16 v[180:181], v222 offset:33280
	ds_read_b64_tr_b16 v[182:183], v222 offset:37376
	s_nop 9
	s_mov_b32 s90, s94
	v_max3_f32 v188, v148, v149, v150
	v_max3_f32 v189, v151, v152, v153
	v_max3_f32 v190, v154, v155, v156
	v_max3_f32 v191, v157, v158, v159
	v_max3_f32 v192, v160, v161, v162
	v_max3_f32 v188, v188, v189, v190
	v_max3_f32 v191, v191, v192, v163
	v_max_f32_e32 v188, v188, v191
	v_add_f32_e32 v188, 0xcb400000, v188
	v_fma_f32 v189, v208, v188, -v237
	v_cmp_gt_f32_e32 vcc, v189, v220
	s_cbranch_vccnz .Lv2_rare_h3
